# kvstate: the four K-row loads of a K-tile issued together (one round trip instead of two)
# baseline (speedup 1.0000x reference)
.LBB0_506:
	v_readfirstlane_b32 s5, v129
	v_lshl_add_u64 v[114:115], s[18:19], 1, v[110:111]
	v_readfirstlane_b32 s6, v164
	s_mov_b32 m0, s5
	v_readfirstlane_b32 s7, v165
	v_lshl_add_u64 v[116:117], v[114:115], 0, s[20:21]
	global_load_lds_dwordx4 v[114:115], off
	s_mov_b32 m0, s6
	v_readfirstlane_b32 s8, v166
	v_add_lshl_u32 v64, v91, s18, 11
	v_lshl_add_u64 v[118:119], v[114:115], 0, s[22:23]
	global_load_lds_dwordx4 v[116:117], off
	s_mov_b32 m0, s7
	v_lshl_add_u64 v[120:121], v[114:115], 0, s[24:25]
	v_lshl_add_u64 v[122:123], v[112:113], 0, v[64:65]
	global_load_lds_dwordx4 v[118:119], off
	s_mov_b32 m0, s8
	v_add_u32_e32 v93, s18, v154
	global_load_lds_dwordx4 v[120:121], off
	global_load_dwordx4 v[248:251], v[122:123], off
	global_load_dwordx4 v[114:117], v[122:123], off offset:16
	global_load_dwordx4 v[118:121], v[122:123], off offset:32
	global_load_dwordx4 v[122:125], v[122:123], off offset:48
	v_sub_u32_e32 v93, 0x7f, v93
	v_cvt_f32_i32_e32 v64, v93
	s_mov_b32 s18, 64
	s_and_b64 vcc, exec, s[0:1]
	s_mov_b64 s[0:1], 0
	v_mul_f32_e32 v64, v95, v64
	v_mul_f32_e32 v64, 0x3fb8aa3b, v64
	v_exp_f32_e32 v64, v64
	s_waitcnt vmcnt(3)
	v_lshlrev_b32_e32 v93, 16, v248
	v_and_b32_e32 v97, 0xffff0000, v248
	v_lshlrev_b32_e32 v99, 16, v249
	v_and_b32_e32 v101, 0xffff0000, v249
	v_lshlrev_b32_e32 v103, 16, v250
	v_and_b32_e32 v105, 0xffff0000, v250
	v_lshlrev_b32_e32 v107, 16, v251
	v_and_b32_e32 v109, 0xffff0000, v251
	v_mul_f32_e32 v93, v64, v93
	v_mul_f32_e32 v97, v64, v97
	v_mul_f32_e32 v99, v64, v99
	v_mul_f32_e32 v101, v64, v101
	v_mul_f32_e32 v103, v64, v103
	v_mul_f32_e32 v105, v64, v105
	v_mul_f32_e32 v107, v64, v107
	v_mul_f32_e32 v109, v64, v109
	v_bfe_u32 v252, v93, 16, 1
	v_bfe_u32 v253, v97, 16, 1
	v_bfe_u32 v254, v99, 16, 1
	v_bfe_u32 v255, v101, 16, 1
	v_bfe_u32 v215, v103, 16, 1
	v_bfe_u32 v217, v105, 16, 1
	v_bfe_u32 v219, v107, 16, 1
	v_bfe_u32 v221, v109, 16, 1
	v_add3_u32 v93, v93, v252, s53
	v_add3_u32 v97, v97, v253, s53
	v_add3_u32 v99, v99, v254, s53
	v_add3_u32 v101, v101, v255, s53
	v_add3_u32 v103, v103, v215, s53
	v_add3_u32 v105, v105, v217, s53
	v_add3_u32 v107, v107, v219, s53
	v_add3_u32 v109, v109, v221, s53
	ds_write_b16_d16_hi v167, v93 offset:16384
	ds_write_b16_d16_hi v167, v97 offset:16512
	ds_write_b16_d16_hi v168, v99 offset:16640
	ds_write_b16_d16_hi v168, v101 offset:16768
	ds_write_b16_d16_hi v169, v103 offset:16896
	ds_write_b16_d16_hi v169, v105 offset:17024
	ds_write_b16_d16_hi v170, v107 offset:17152
	ds_write_b16_d16_hi v170, v109 offset:17280
	s_waitcnt vmcnt(0)
	v_lshlrev_b32_e32 v93, 16, v114
	v_and_b32_e32 v97, 0xffff0000, v114
	v_lshlrev_b32_e32 v99, 16, v115
	v_and_b32_e32 v101, 0xffff0000, v115
	v_lshlrev_b32_e32 v103, 16, v116
	v_and_b32_e32 v105, 0xffff0000, v116
	v_lshlrev_b32_e32 v107, 16, v117
	v_and_b32_e32 v109, 0xffff0000, v117
	v_lshlrev_b32_e32 v114, 16, v118
	v_and_b32_e32 v115, 0xffff0000, v118
	v_lshlrev_b32_e32 v116, 16, v119
	v_and_b32_e32 v117, 0xffff0000, v119
	v_lshlrev_b32_e32 v118, 16, v120
	v_and_b32_e32 v119, 0xffff0000, v120
	v_lshlrev_b32_e32 v120, 16, v121
	v_and_b32_e32 v121, 0xffff0000, v121
	v_lshlrev_b32_e32 v126, 16, v122
	v_and_b32_e32 v122, 0xffff0000, v122
	v_lshlrev_b32_e32 v127, 16, v123
	v_and_b32_e32 v123, 0xffff0000, v123
	v_lshlrev_b32_e32 v140, 16, v124
	v_and_b32_e32 v124, 0xffff0000, v124
	v_lshlrev_b32_e32 v141, 16, v125
	v_and_b32_e32 v125, 0xffff0000, v125
	v_mul_f32_e32 v93, v64, v93
	v_mul_f32_e32 v97, v64, v97
	v_mul_f32_e32 v99, v64, v99
	v_mul_f32_e32 v101, v64, v101
	v_mul_f32_e32 v103, v64, v103
	v_mul_f32_e32 v105, v64, v105
	v_mul_f32_e32 v107, v64, v107
	v_mul_f32_e32 v109, v64, v109
	v_mul_f32_e32 v114, v64, v114
	v_mul_f32_e32 v115, v64, v115
	v_mul_f32_e32 v116, v64, v116
	v_mul_f32_e32 v117, v64, v117
	v_mul_f32_e32 v118, v64, v118
	v_mul_f32_e32 v119, v64, v119
	v_mul_f32_e32 v120, v64, v120
	v_mul_f32_e32 v121, v64, v121
	v_mul_f32_e32 v126, v64, v126
	v_mul_f32_e32 v122, v64, v122
	v_mul_f32_e32 v127, v64, v127
	v_mul_f32_e32 v123, v64, v123
	v_mul_f32_e32 v140, v64, v140
	v_mul_f32_e32 v124, v64, v124
	v_mul_f32_e32 v141, v64, v141
	v_mul_f32_e32 v64, v64, v125
	v_bfe_u32 v125, v93, 16, 1
	v_bfe_u32 v142, v97, 16, 1
	v_bfe_u32 v143, v99, 16, 1
	v_bfe_u32 v144, v101, 16, 1
	v_bfe_u32 v145, v103, 16, 1
	v_bfe_u32 v146, v105, 16, 1
	v_bfe_u32 v147, v107, 16, 1
	v_bfe_u32 v182, v109, 16, 1
	v_bfe_u32 v183, v114, 16, 1
	v_bfe_u32 v184, v115, 16, 1
	v_bfe_u32 v185, v116, 16, 1
	v_bfe_u32 v186, v117, 16, 1
	v_bfe_u32 v187, v118, 16, 1
	v_bfe_u32 v188, v119, 16, 1
	v_bfe_u32 v189, v120, 16, 1
	v_bfe_u32 v190, v121, 16, 1
	v_bfe_u32 v191, v126, 16, 1
	v_bfe_u32 v192, v122, 16, 1
	v_bfe_u32 v193, v127, 16, 1
	v_bfe_u32 v194, v123, 16, 1
	v_bfe_u32 v195, v140, 16, 1
	v_bfe_u32 v196, v124, 16, 1
	v_bfe_u32 v197, v141, 16, 1
	v_bfe_u32 v198, v64, 16, 1
	v_add3_u32 v93, v93, v125, s53
	v_add3_u32 v97, v97, v142, s53
	v_add3_u32 v99, v99, v143, s53
	v_add3_u32 v101, v101, v144, s53
	v_add3_u32 v103, v103, v145, s53
	v_add3_u32 v105, v105, v146, s53
	v_add3_u32 v107, v107, v147, s53
	v_add3_u32 v109, v109, v182, s53
	v_add3_u32 v114, v114, v183, s53
	v_add3_u32 v115, v115, v184, s53
	v_add3_u32 v116, v116, v185, s53
	v_add3_u32 v117, v117, v186, s53
	v_add3_u32 v118, v118, v187, s53
	v_add3_u32 v119, v119, v188, s53
	v_add3_u32 v120, v120, v189, s53
	v_add3_u32 v121, v121, v190, s53
	v_add3_u32 v125, v126, v191, s53
	v_add3_u32 v122, v122, v192, s53
	v_add3_u32 v126, v127, v193, s53
	v_add3_u32 v123, v123, v194, s53
	v_add3_u32 v127, v140, v195, s53
	v_add3_u32 v124, v124, v196, s53
	v_add3_u32 v140, v141, v197, s53
	v_add3_u32 v64, v64, v198, s53
	ds_write_b16_d16_hi v171, v93 offset:17408
	ds_write_b16_d16_hi v171, v97 offset:17536
	ds_write_b16_d16_hi v172, v99 offset:17664
	ds_write_b16_d16_hi v172, v101 offset:17792
	ds_write_b16_d16_hi v173, v103 offset:17920
	ds_write_b16_d16_hi v173, v105 offset:18048
	ds_write_b16_d16_hi v174, v107 offset:18176
	ds_write_b16_d16_hi v174, v109 offset:18304
	ds_write_b16_d16_hi v167, v114 offset:18432
	ds_write_b16_d16_hi v167, v115 offset:18560
	ds_write_b16_d16_hi v168, v116 offset:18688
	ds_write_b16_d16_hi v168, v117 offset:18816
	ds_write_b16_d16_hi v169, v118 offset:18944
	ds_write_b16_d16_hi v169, v119 offset:19072
	ds_write_b16_d16_hi v170, v120 offset:19200
	ds_write_b16_d16_hi v170, v121 offset:19328
	ds_write_b16_d16_hi v171, v125 offset:19456
	ds_write_b16_d16_hi v171, v122 offset:19584
	ds_write_b16_d16_hi v172, v126 offset:19712
	ds_write_b16_d16_hi v172, v123 offset:19840
	ds_write_b16_d16_hi v173, v127 offset:19968
	ds_write_b16_d16_hi v173, v124 offset:20096
	ds_write_b16_d16_hi v174, v140 offset:20224
	ds_write_b16_d16_hi v174, v64 offset:20352
	s_waitcnt vmcnt(0)
	s_waitcnt lgkmcnt(0)
	s_barrier
	ds_read_b128 v[114:117], v175
	ds_read_b128 v[118:121], v176 offset:16384
	ds_read_b128 v[122:125], v176 offset:18432
	ds_read_b128 v[140:143], v176 offset:20480
	ds_read_b128 v[144:147], v175 offset:2048
	ds_read_b128 v[182:185], v176 offset:22528
	ds_read_b128 v[186:189], v176 offset:24576
	ds_read_b128 v[190:193], v176 offset:26624
	ds_read_b128 v[194:197], v176 offset:28672
	ds_read_b128 v[198:201], v176 offset:30720
	ds_read_b128 v[202:205], v177
	ds_read_b128 v[206:209], v177 offset:2048
	ds_read_b128 v[210:213], v178 offset:16384
	ds_read_b128 v[214:217], v178 offset:18432
	ds_read_b128 v[218:221], v178 offset:20480
	ds_read_b128 v[222:225], v178 offset:22528
	ds_read_b128 v[226:229], v178 offset:24576
	ds_read_b128 v[230:233], v178 offset:26624
	ds_read_b128 v[234:237], v178 offset:28672
	ds_read_b128 v[238:241], v178 offset:30720
	s_waitcnt lgkmcnt(14)
	v_mfma_f32_16x16x32_bf16 v[0:3], v[114:117], v[118:121], v[0:3]
	s_waitcnt lgkmcnt(0)
	s_barrier
	v_mfma_f32_16x16x32_bf16 v[36:39], v[114:117], v[122:125], v[36:39]
	v_mfma_f32_16x16x32_bf16 v[40:43], v[114:117], v[140:143], v[40:43]
	v_mfma_f32_16x16x32_bf16 v[44:47], v[114:117], v[182:185], v[44:47]
	v_mfma_f32_16x16x32_bf16 v[48:51], v[114:117], v[186:189], v[48:51]
	v_mfma_f32_16x16x32_bf16 v[52:55], v[114:117], v[190:193], v[52:55]
	v_mfma_f32_16x16x32_bf16 v[56:59], v[114:117], v[194:197], v[56:59]
	v_mfma_f32_16x16x32_bf16 v[60:63], v[114:117], v[198:201], v[60:63]
	v_mfma_f32_16x16x32_bf16 v[4:7], v[144:147], v[118:121], v[4:7]
	v_mfma_f32_16x16x32_bf16 v[8:11], v[144:147], v[122:125], v[8:11]
	v_mfma_f32_16x16x32_bf16 v[12:15], v[144:147], v[140:143], v[12:15]
	v_mfma_f32_16x16x32_bf16 v[16:19], v[144:147], v[182:185], v[16:19]
	v_mfma_f32_16x16x32_bf16 v[20:23], v[144:147], v[186:189], v[20:23]
	v_mfma_f32_16x16x32_bf16 v[24:27], v[144:147], v[190:193], v[24:27]
	v_mfma_f32_16x16x32_bf16 v[28:31], v[144:147], v[194:197], v[28:31]
	v_mfma_f32_16x16x32_bf16 v[32:35], v[144:147], v[198:201], v[32:35]
	v_mfma_f32_16x16x32_bf16 v[0:3], v[202:205], v[210:213], v[0:3]
	v_mfma_f32_16x16x32_bf16 v[36:39], v[202:205], v[214:217], v[36:39]
	v_mfma_f32_16x16x32_bf16 v[40:43], v[202:205], v[218:221], v[40:43]
	v_mfma_f32_16x16x32_bf16 v[44:47], v[202:205], v[222:225], v[44:47]
	v_mfma_f32_16x16x32_bf16 v[48:51], v[202:205], v[226:229], v[48:51]
	v_mfma_f32_16x16x32_bf16 v[52:55], v[202:205], v[230:233], v[52:55]
	v_mfma_f32_16x16x32_bf16 v[56:59], v[202:205], v[234:237], v[56:59]
	v_mfma_f32_16x16x32_bf16 v[60:63], v[202:205], v[238:241], v[60:63]
	v_mfma_f32_16x16x32_bf16 v[4:7], v[206:209], v[210:213], v[4:7]
	v_mfma_f32_16x16x32_bf16 v[8:11], v[206:209], v[214:217], v[8:11]
	v_mfma_f32_16x16x32_bf16 v[12:15], v[206:209], v[218:221], v[12:15]
	v_mfma_f32_16x16x32_bf16 v[16:19], v[206:209], v[222:225], v[16:19]
	v_mfma_f32_16x16x32_bf16 v[20:23], v[206:209], v[226:229], v[20:23]
	v_mfma_f32_16x16x32_bf16 v[24:27], v[206:209], v[230:233], v[24:27]
	v_mfma_f32_16x16x32_bf16 v[28:31], v[206:209], v[234:237], v[28:31]
	v_mfma_f32_16x16x32_bf16 v[32:35], v[206:209], v[238:241], v[32:35]
	s_cbranch_vccnz .LBB0_506
	v_add_u32_e32 v91, 0x400, v148
	ds_write2_b32 v148, v0, v36 offset1:16
	ds_write2_b32 v148, v1, v37 offset0:128 offset1:144
	ds_write2_b32 v91, v2, v38 offset1:16
	ds_write2_b32 v91, v3, v39 offset0:128 offset1:144
	ds_write2_b32 v148, v40, v44 offset0:32 offset1:48
	ds_write2_b32 v148, v41, v45 offset0:160 offset1:176
	ds_write2_b32 v91, v42, v46 offset0:32 offset1:48
	ds_write2_b32 v91, v43, v47 offset0:160 offset1:176
	ds_write2_b32 v148, v48, v52 offset0:64 offset1:80
	ds_write2_b32 v148, v49, v53 offset0:192 offset1:208
	ds_write2_b32 v91, v50, v54 offset0:64 offset1:80
	ds_write2_b32 v91, v51, v55 offset0:192 offset1:208
	ds_write2st64_b32 v149, v56, v57 offset1:2
	ds_write2st64_b32 v149, v58, v59 offset0:4 offset1:6
	ds_write2st64_b32 v150, v60, v61 offset1:2
	ds_write2st64_b32 v150, v62, v63 offset0:4 offset1:6
	ds_read_b128 v[0:3], v67 offset:16
	ds_read_b128 v[36:39], v67
	s_lshl_b32 s0, s4, 15
	s_add_u32 s0, s33, s0
	s_addc_u32 s1, s44, 0
	s_waitcnt lgkmcnt(1)
	s_waitcnt lgkmcnt(0)
	v_cvt_pk_bf16_f32 v3, v2, v3
	v_cvt_pk_bf16_f32 v2, v0, v1
	v_cvt_pk_bf16_f32 v1, v38, v39
	v_cvt_pk_bf16_f32 v0, v36, v37
	ds_read_b128 v[36:39], v151
	ds_read_b128 v[40:43], v151 offset:16
	v_mov_b32_e32 v95, v65
	v_lshl_add_u64 v[44:45], s[0:1], 0, v[94:95]
	v_lshlrev_b32_e32 v64, 1, v66
	v_lshl_add_u64 v[44:45], v[44:45], 0, v[64:65]
	global_store_dwordx4 v[44:45], v[0:3], off
	s_waitcnt lgkmcnt(1)
	s_waitcnt lgkmcnt(0)
	v_cvt_pk_bf16_f32 v3, v42, v43
	v_cvt_pk_bf16_f32 v2, v40, v41
	v_cvt_pk_bf16_f32 v1, v38, v39
	v_cvt_pk_bf16_f32 v0, v36, v37
	ds_read_b128 v[36:39], v160
	ds_read_b128 v[40:43], v160 offset:16
	v_mov_b32_e32 v97, v65
	v_lshl_add_u64 v[44:45], s[0:1], 0, v[96:97]
	v_lshl_add_u64 v[44:45], v[44:45], 0, v[64:65]
	global_store_dwordx4 v[44:45], v[0:3], off
	s_waitcnt lgkmcnt(1)
	s_waitcnt lgkmcnt(0)
	v_cvt_pk_bf16_f32 v3, v42, v43
	v_cvt_pk_bf16_f32 v2, v40, v41
	v_cvt_pk_bf16_f32 v1, v38, v39
	v_cvt_pk_bf16_f32 v0, v36, v37
	ds_read_b128 v[36:39], v161
	ds_read_b128 v[40:43], v161 offset:16
	v_mov_b32_e32 v99, v65
	v_lshl_add_u64 v[44:45], s[0:1], 0, v[98:99]
	v_lshl_add_u64 v[44:45], v[44:45], 0, v[64:65]
	global_store_dwordx4 v[44:45], v[0:3], off
	s_waitcnt lgkmcnt(1)
	s_waitcnt lgkmcnt(0)
	v_mov_b32_e32 v101, v65
	v_cvt_pk_bf16_f32 v3, v42, v43
	v_cvt_pk_bf16_f32 v0, v36, v37
	v_lshl_add_u64 v[36:37], s[0:1], 0, v[100:101]
	v_cvt_pk_bf16_f32 v2, v40, v41
	v_cvt_pk_bf16_f32 v1, v38, v39
	v_lshl_add_u64 v[36:37], v[36:37], 0, v[64:65]
	global_store_dwordx4 v[36:37], v[0:3], off
	ds_write2_b32 v148, v4, v8 offset1:16
	ds_write2_b32 v148, v5, v9 offset0:128 offset1:144
	ds_write2_b32 v91, v6, v10 offset1:16
	ds_write2_b32 v91, v7, v11 offset0:128 offset1:144
	ds_write2_b32 v148, v12, v16 offset0:32 offset1:48
	ds_write2_b32 v148, v13, v17 offset0:160 offset1:176
	ds_write2_b32 v91, v14, v18 offset0:32 offset1:48
	ds_write2_b32 v91, v15, v19 offset0:160 offset1:176
	ds_write2_b32 v148, v20, v24 offset0:64 offset1:80
	ds_write2_b32 v148, v21, v25 offset0:192 offset1:208
	ds_write2_b32 v91, v22, v26 offset0:64 offset1:80
	ds_write2_b32 v91, v23, v27 offset0:192 offset1:208
	ds_write2st64_b32 v149, v28, v29 offset1:2
	ds_write2st64_b32 v149, v30, v31 offset0:4 offset1:6
	ds_write2st64_b32 v150, v32, v33 offset1:2
	ds_write2st64_b32 v150, v34, v35 offset0:4 offset1:6
	ds_read_b128 v[0:3], v67 offset:16
	ds_read_b128 v[4:7], v67
	v_mov_b32_e32 v103, v65
	v_mov_b32_e32 v105, v65
	v_mov_b32_e32 v107, v65
	s_waitcnt lgkmcnt(1)
	s_waitcnt lgkmcnt(0)
	v_cvt_pk_bf16_f32 v3, v2, v3
	v_cvt_pk_bf16_f32 v2, v0, v1
	v_cvt_pk_bf16_f32 v1, v6, v7
	v_cvt_pk_bf16_f32 v0, v4, v5
	ds_read_b128 v[4:7], v151
	ds_read_b128 v[8:11], v151 offset:16
	v_lshl_add_u64 v[12:13], s[0:1], 0, v[102:103]
	v_lshl_add_u64 v[12:13], v[12:13], 0, v[64:65]
	global_store_dwordx4 v[12:13], v[0:3], off
	s_waitcnt lgkmcnt(1)
	s_waitcnt lgkmcnt(0)
	v_cvt_pk_bf16_f32 v3, v10, v11
	v_cvt_pk_bf16_f32 v2, v8, v9
	v_cvt_pk_bf16_f32 v1, v6, v7
	v_cvt_pk_bf16_f32 v0, v4, v5
	ds_read_b128 v[4:7], v160
	ds_read_b128 v[8:11], v160 offset:16
	v_lshl_add_u64 v[12:13], s[0:1], 0, v[104:105]
	v_lshl_add_u64 v[12:13], v[12:13], 0, v[64:65]
	global_store_dwordx4 v[12:13], v[0:3], off
	s_waitcnt lgkmcnt(1)
	s_waitcnt lgkmcnt(0)
	v_cvt_pk_bf16_f32 v3, v10, v11
	v_cvt_pk_bf16_f32 v2, v8, v9
	v_cvt_pk_bf16_f32 v1, v6, v7
	v_cvt_pk_bf16_f32 v0, v4, v5
	ds_read_b128 v[4:7], v161
	ds_read_b128 v[8:11], v161 offset:16
	v_lshl_add_u64 v[12:13], s[0:1], 0, v[106:107]
	v_lshl_add_u64 v[12:13], v[12:13], 0, v[64:65]
	global_store_dwordx4 v[12:13], v[0:3], off
	s_waitcnt lgkmcnt(1)
	s_waitcnt lgkmcnt(0)
	v_mov_b32_e32 v109, v65
	v_cvt_pk_bf16_f32 v3, v10, v11
	v_cvt_pk_bf16_f32 v0, v4, v5
	v_lshl_add_u64 v[4:5], s[0:1], 0, v[108:109]
	v_cvt_pk_bf16_f32 v2, v8, v9
	v_cvt_pk_bf16_f32 v1, v6, v7
	v_lshl_add_u64 v[4:5], v[4:5], 0, v[64:65]
	global_store_dwordx4 v[4:5], v[0:3], off
	s_branch .LBB0_502
